# LayerNorm gain/bias loads hoisted out of the row loops (no per-chunk vmcnt(0)); X1B stores cacheable
# speedup vs baseline: 1.0026x; 1.0017x over previous
; __device__ __forceinline__ unsigned pk2(float lo, float hi) { unsigned r; asm("v_cvt_pk_bf16_f32 %0, %1, %2" : "=v"(r) : "v"(lo), "v"(hi)); return r; }
; __device__ __forceinline__ void phase_ln(const float* res, const bf16_t* br, float* out, const float* gam, const float* bet, bf16_t* xb) {
;     const int tid = threadIdx.x, lane = tid & 63, wave = tid >> 6;
;     for (int row = blockIdx.x * NWAVES + wave; row < T; row += gridDim.x * NWAVES) {
;         const f32x4* xr = (const f32x4*)(res + (size_t)row * DM) + lane; const u32x2* brr = (const u32x2*)(br + (size_t)row * DM) + lane;
;         f32x4 v[8]; float s = 0.f;
; #pragma unroll
;         for (int j = 0; j < 8; ++j) { const f32x4 xv = __builtin_nontemporal_load(xr + 64 * j); const u32x2 bw = __builtin_nontemporal_load(brr + 64 * j);
;             v[j] = xv * ALPHA + (f32x4){bflo(bw.x), bfhi(bw.x), bflo(bw.y), bfhi(bw.y)}; s += (v[j][0] + v[j][1]) + (v[j][2] + v[j][3]); }
;         const float mu = wave_sum(s) * (1.0f / DM); float q = 0.f;
; #pragma unroll
;         for (int j = 0; j < 8; ++j) { v[j] = v[j] - mu; q += (v[j][0] * v[j][0] + v[j][1] * v[j][1]) + (v[j][2] * v[j][2] + v[j][3] * v[j][3]); }
;         const float rstd = 1.0f / sqrtf(wave_sum(q) * (1.0f / DM) + LN_EPS);
;         f32x4* orow = (f32x4*)(out + (size_t)row * DM) + lane;
; #pragma unroll
;         for (int j = 0; j < 8; ++j) { const f32x4 gv = *((const f32x4*)gam + 64 * j + lane), bv = *((const f32x4*)bet + 64 * j + lane);
;             const f32x4 y = v[j] * rstd * gv + bv; __builtin_nontemporal_store(y, orow + 64 * j);
;             if (xb) { u32x2 wv; wv.x = pk2(y[0], y[1]); wv.y = pk2(y[2], y[3]); __builtin_nontemporal_store(wv, (u32x2*)(xb + (size_t)row * DM) + 64 * j + lane); } }
.LBB0_811:
	v_readlane_b32 s4, v246, 12
	s_cmp_lt_i32 s4, 9
	s_cselect_b64 s[2:3], -1, 0
	s_and_b64 s[0:1], s[2:3], s[0:1]
	s_andn2_b64 vcc, exec, s[0:1]
	v_readlane_b32 s5, v246, 13
	v_readlane_b32 s6, v246, 14
	v_readlane_b32 s7, v246, 15
	s_cbranch_vccnz .LBB0_816
	v_readlane_b32 s0, v246, 0
	v_readlane_b32 s1, v246, 1
	s_nop 0
	v_lshl_add_u32 v0, s0, 3, v159
	s_mov_b32 s0, 0x8000
	v_cmp_gt_i32_e32 vcc, s0, v0
	s_and_saveexec_b64 s[4:5], vcc
	s_cbranch_execz .LBB0_815
	v_and_b32_e32 v1, 63, v144
	s_waitcnt vmcnt(0)
	v_lshlrev_b32_e32 v10, 4, v1
	v_lshlrev_b32_e32 v4, 3, v1
	v_mbcnt_lo_u32_b32 v1, -1, 0
	v_mbcnt_hi_u32_b32 v1, -1, v1
	v_and_b32_e32 v6, 64, v1
	v_add_u32_e32 v6, 64, v6
	v_xor_b32_e32 v7, 1, v1
	v_cmp_lt_i32_e32 vcc, v7, v6
	v_readlane_b32 s8, v246, 2
	v_mov_b32_e32 v11, 0
	v_cndmask_b32_e32 v7, v1, v7, vcc
	v_lshlrev_b32_e32 v66, 2, v7
	v_xor_b32_e32 v7, 2, v1
	v_cmp_lt_i32_e32 vcc, v7, v6
	v_readlane_b32 s0, v246, 10
	v_readlane_b32 s9, v246, 3
	v_cndmask_b32_e32 v7, v1, v7, vcc
	v_lshlrev_b32_e32 v67, 2, v7
	v_xor_b32_e32 v7, 4, v1
	v_cmp_lt_i32_e32 vcc, v7, v6
	v_readlane_b32 s10, v246, 4
	v_readlane_b32 s11, v246, 5
	v_cndmask_b32_e32 v7, v1, v7, vcc
	v_lshlrev_b32_e32 v68, 2, v7
	v_xor_b32_e32 v7, 8, v1
	v_cmp_lt_i32_e32 vcc, v7, v6
	v_readlane_b32 s12, v246, 6
	v_readlane_b32 s13, v246, 7
	v_cndmask_b32_e32 v7, v1, v7, vcc
	v_lshlrev_b32_e32 v69, 2, v7
	v_xor_b32_e32 v7, 16, v1
	v_cmp_lt_i32_e32 vcc, v7, v6
	v_readlane_b32 s14, v246, 8
	v_readlane_b32 s15, v246, 9
	v_cndmask_b32_e32 v7, v1, v7, vcc
	v_lshlrev_b32_e32 v70, 2, v7
	v_xor_b32_e32 v7, 32, v1
	v_cmp_lt_i32_e32 vcc, v7, v6
	s_waitcnt lgkmcnt(0)
	v_lshl_add_u64 v[2:3], s[16:17], 0, v[10:11]
	v_mov_b32_e32 v5, v11
	v_readlane_b32 s1, v246, 11
	v_cndmask_b32_e32 v1, v1, v7, vcc
	v_lshl_add_u64 v[6:7], s[14:15], 0, v[10:11]
	v_readlane_b32 s8, v246, 25
	v_lshl_add_u64 v[12:13], s[0:1], 0, v[4:5]
	s_mov_b64 s[0:1], 0x10800000
	v_readlane_b32 s9, v246, 26
	v_readlane_b32 s14, v246, 31
	v_readlane_b32 s15, v246, 32
	v_readlane_b32 s16, v246, 33
	v_readlane_b32 s17, v246, 34
	v_lshl_add_u64 v[4:5], v[12:13], 0, s[0:1]
	s_mov_b64 s[6:7], s[14:15]
	s_mov_b64 s[8:9], s[16:17]
	s_mov_b64 s[0:1], 0x8800000
	v_lshl_add_u64 v[8:9], s[6:7], 0, v[10:11]
	v_lshl_add_u64 v[10:11], s[8:9], 0, v[10:11]
	v_lshl_add_u64 v[12:13], v[12:13], 0, s[0:1]
	s_mov_b64 s[0:1], 0x1000
	v_lshl_add_u64 v[14:15], v[8:9], 0, s[0:1]
	v_lshl_add_u64 v[16:17], v[10:11], 0, s[0:1]
	s_mov_b64 s[0:1], 0x1400
	v_lshl_add_u64 v[18:19], v[8:9], 0, s[0:1]
	v_lshl_add_u64 v[20:21], v[10:11], 0, s[0:1]
	s_mov_b64 s[0:1], 0x1800
	v_readlane_b32 s10, v246, 27
	v_readlane_b32 s11, v246, 28
	v_readlane_b32 s12, v246, 29
	v_lshl_add_u64 v[22:23], v[8:9], 0, s[0:1]
	v_lshl_add_u64 v[24:25], v[10:11], 0, s[0:1]
	s_mov_b64 s[0:1], 0x1c00
	v_lshlrev_b32_e32 v71, 2, v1
	v_lshl_add_u64 v[26:27], v[8:9], 0, s[0:1]
	v_lshl_add_u64 v[28:29], v[10:11], 0, s[0:1]
	s_lshl_b32 s9, s34, 3
	s_mov_b64 s[6:7], 0
	s_mov_b32 s8, 0x3f9837f0
	s_movk_i32 s10, 0x1000
	v_mov_b32_e32 v72, 0x3727c5ac
	s_mov_b32 s11, 0xf800000
	v_mov_b32_e32 v73, 0x260
	s_movk_i32 s12, 0x7fff
	v_readlane_b32 s13, v246, 30
	v_readlane_b32 s18, v246, 35
	v_readlane_b32 s19, v246, 36
	v_readlane_b32 s20, v246, 37
	v_readlane_b32 s21, v246, 38
	v_readlane_b32 s22, v246, 39
	v_readlane_b32 s23, v246, 40
	global_load_dwordx4 v[160:163], v[8:9], off
	global_load_dwordx4 v[164:167], v[10:11], off
	global_load_dwordx4 v[168:171], v[8:9], off offset:1024
	global_load_dwordx4 v[172:175], v[10:11], off offset:1024
	global_load_dwordx4 v[176:179], v[8:9], off offset:2048
	global_load_dwordx4 v[180:183], v[10:11], off offset:2048
	global_load_dwordx4 v[184:187], v[8:9], off offset:3072
	global_load_dwordx4 v[188:191], v[10:11], off offset:3072
	global_load_dwordx4 v[192:195], v[14:15], off
	global_load_dwordx4 v[196:199], v[16:17], off
	global_load_dwordx4 v[200:203], v[18:19], off
	global_load_dwordx4 v[204:207], v[20:21], off
	global_load_dwordx4 v[208:211], v[22:23], off
	global_load_dwordx4 v[212:215], v[24:25], off
	global_load_dwordx4 v[216:219], v[26:27], off
	global_load_dwordx4 v[220:223], v[28:29], off
	s_waitcnt vmcnt(0)
.LBB0_814:
	v_ashrrev_i32_e32 v1, 31, v0
	v_lshlrev_b64 v[30:31], 12, v[0:1]
	v_lshl_add_u64 v[50:51], v[4:5], 0, v[30:31]
	v_lshlrev_b64 v[48:49], 13, v[0:1]
	global_load_dwordx2 v[52:53], v[50:51], off nt
	global_load_dwordx2 v[54:55], v[50:51], off offset:512 nt
	global_load_dwordx2 v[56:57], v[50:51], off offset:1024 nt
	global_load_dwordx2 v[58:59], v[50:51], off offset:1536 nt
	global_load_dwordx2 v[60:61], v[50:51], off offset:2048 nt
	global_load_dwordx2 v[62:63], v[50:51], off offset:2560 nt
	v_lshl_add_u64 v[64:65], v[2:3], 0, v[48:49]
	global_load_dwordx4 v[32:35], v[64:65], off nt
	global_load_dwordx4 v[36:39], v[64:65], off offset:1024 nt
	global_load_dwordx4 v[40:43], v[64:65], off offset:2048 nt
	global_load_dwordx4 v[44:47], v[64:65], off offset:3072 nt
	v_add_co_u32_e32 v64, vcc, s10, v64
	v_add_u32_e32 v0, s9, v0
	s_nop 0
	v_addc_co_u32_e32 v65, vcc, 0, v65, vcc
	global_load_dwordx4 v[74:77], v[64:65], off nt
	global_load_dwordx4 v[78:81], v[64:65], off offset:1024 nt
	global_load_dwordx2 v[90:91], v[50:51], off offset:3072 nt
	global_load_dwordx4 v[82:85], v[64:65], off offset:2048 nt
	global_load_dwordx2 v[92:93], v[50:51], off offset:3584 nt
	global_load_dwordx4 v[86:89], v[64:65], off offset:3072 nt
	s_waitcnt vmcnt(15)
	v_lshlrev_b32_e32 v50, 16, v52
	v_and_b32_e32 v51, 0xffff0000, v52
	v_lshlrev_b32_e32 v52, 16, v53
	v_and_b32_e32 v53, 0xffff0000, v53
	s_waitcnt vmcnt(14)
; __device__ __forceinline__ void phase_ln(const float* res, const bf16_t* br, float* out, const float* gam, const float* bet, bf16_t* xb) {
;     ...
;     for (int row = blockIdx.x * NWAVES + wave; row < T; row += gridDim.x * NWAVES) {
;         const f32x4* xr = (const f32x4*)(res + (size_t)row * DM) + lane; const u32x2* brr = (const u32x2*)(br + (size_t)row * DM) + lane;
;         f32x4 v[8]; float s = 0.f;
; #pragma unroll
;         for (int j = 0; j < 8; ++j) { const f32x4 xv = __builtin_nontemporal_load(xr + 64 * j); const u32x2 bw = __builtin_nontemporal_load(brr + 64 * j);
;             v[j] = xv * ALPHA + (f32x4){bflo(bw.x), bfhi(bw.x), bflo(bw.y), bfhi(bw.y)}; s += (v[j][0] + v[j][1]) + (v[j][2] + v[j][3]); }
;         const float mu = wave_sum(s) * (1.0f / DM); float q = 0.f;
	v_lshlrev_b32_e32 v94, 16, v54
	v_and_b32_e32 v95, 0xffff0000, v54
	v_lshlrev_b32_e32 v54, 16, v55
	v_and_b32_e32 v55, 0xffff0000, v55
	s_waitcnt vmcnt(13)
	v_lshlrev_b32_e32 v96, 16, v56
	v_and_b32_e32 v97, 0xffff0000, v56
	v_lshlrev_b32_e32 v56, 16, v57
	v_and_b32_e32 v57, 0xffff0000, v57
	s_waitcnt vmcnt(12)
	v_lshlrev_b32_e32 v98, 16, v58
	v_and_b32_e32 v99, 0xffff0000, v58
	v_lshlrev_b32_e32 v100, 16, v59
	v_and_b32_e32 v101, 0xffff0000, v59
	s_waitcnt vmcnt(11)
	v_lshlrev_b32_e32 v102, 16, v60
	v_and_b32_e32 v103, 0xffff0000, v60
	v_lshlrev_b32_e32 v104, 16, v61
	v_and_b32_e32 v105, 0xffff0000, v61
	s_waitcnt vmcnt(10)
	v_lshlrev_b32_e32 v106, 16, v62
	v_and_b32_e32 v107, 0xffff0000, v62
	v_lshlrev_b32_e32 v108, 16, v63
	v_and_b32_e32 v109, 0xffff0000, v63
	s_waitcnt vmcnt(9)
	v_pk_fma_f32 v[62:63], v[34:35], s[8:9], v[52:53] op_sel_hi:[1,0,1]
	v_pk_fma_f32 v[64:65], v[32:33], s[8:9], v[50:51] op_sel_hi:[1,0,1]
	s_waitcnt vmcnt(8)
	v_pk_fma_f32 v[58:59], v[38:39], s[8:9], v[54:55] op_sel_hi:[1,0,1]
	v_pk_fma_f32 v[60:61], v[36:37], s[8:9], v[94:95] op_sel_hi:[1,0,1]
	s_waitcnt vmcnt(7)
	v_pk_fma_f32 v[54:55], v[42:43], s[8:9], v[56:57] op_sel_hi:[1,0,1]
	v_pk_fma_f32 v[56:57], v[40:41], s[8:9], v[96:97] op_sel_hi:[1,0,1]
	s_waitcnt vmcnt(6)
	v_pk_fma_f32 v[50:51], v[46:47], s[8:9], v[100:101] op_sel_hi:[1,0,1]
	v_pk_fma_f32 v[52:53], v[44:45], s[8:9], v[98:99] op_sel_hi:[1,0,1]
	v_mov_b32_e32 v32, v64
	v_mov_b32_e32 v33, v60
	v_mov_b32_e32 v34, v65
	v_mov_b32_e32 v35, v61
	v_mov_b32_e32 v44, v62
	v_mov_b32_e32 v45, v58
	v_mov_b32_e32 v46, v63
	v_mov_b32_e32 v47, v59
	s_waitcnt vmcnt(5)
	v_pk_fma_f32 v[40:41], v[76:77], s[8:9], v[104:105] op_sel_hi:[1,0,1]
	v_pk_fma_f32 v[42:43], v[74:75], s[8:9], v[102:103] op_sel_hi:[1,0,1]
	v_pk_mov_b32 v[74:75], v[56:57], v[54:55] op_sel:[1,0]
	v_mov_b32_e32 v76, v56
	v_mov_b32_e32 v77, v55
	v_pk_add_f32 v[32:33], v[32:33], v[34:35]
	v_pk_add_f32 v[34:35], v[44:45], v[46:47]
	v_pk_add_f32 v[44:45], v[74:75], v[76:77]
	v_pk_add_f32 v[32:33], v[32:33], v[34:35]
	v_pk_add_f32 v[34:35], v[44:45], v[44:45] op_sel:[0,1] op_sel_hi:[1,0]
	v_add_f32_e32 v1, 0, v32
	s_waitcnt vmcnt(4)
	v_pk_fma_f32 v[36:37], v[78:79], s[8:9], v[106:107] op_sel_hi:[1,0,1]
	v_pk_fma_f32 v[38:39], v[80:81], s[8:9], v[108:109] op_sel_hi:[1,0,1]
	v_add_f32_e32 v78, v52, v53
	v_add_f32_e32 v80, v50, v51
	v_mov_b32_e32 v95, v42
	v_mov_b32_e32 v79, v40
	v_mov_b32_e32 v81, v41
	v_mov_b32_e32 v35, v43
	v_add_f32_e32 v94, v1, v33
	v_pk_add_f32 v[46:47], v[78:79], v[80:81]
	v_pk_add_f32 v[32:33], v[94:95], v[34:35]
	v_pk_mov_b32 v[96:97], v[36:37], v[38:39] op_sel:[1,0]
	v_pk_add_f32 v[32:33], v[32:33], v[46:47]
	v_mov_b32_e32 v98, v36
	v_mov_b32_e32 v99, v39
	v_pk_add_f32 v[76:77], v[32:33], v[32:33] op_sel:[0,1] op_sel_hi:[1,0]
	s_waitcnt vmcnt(3)
	v_lshlrev_b32_e32 v32, 16, v90
	v_and_b32_e32 v33, 0xffff0000, v90
	v_lshlrev_b32_e32 v34, 16, v91
	v_and_b32_e32 v35, 0xffff0000, v91
	v_pk_add_f32 v[74:75], v[96:97], v[98:99]
	s_waitcnt vmcnt(2)
	v_pk_fma_f32 v[44:45], v[84:85], s[8:9], v[34:35] op_sel_hi:[1,0,1]
	v_pk_fma_f32 v[46:47], v[82:83], s[8:9], v[32:33] op_sel_hi:[1,0,1]
	s_waitcnt vmcnt(1)
	v_lshlrev_b32_e32 v34, 16, v92
	v_and_b32_e32 v35, 0xffff0000, v92
	v_lshlrev_b32_e32 v32, 16, v93
	v_and_b32_e32 v33, 0xffff0000, v93
	v_pk_add_f32 v[74:75], v[74:75], v[74:75] op_sel:[0,1] op_sel_hi:[1,0]
	s_waitcnt vmcnt(0)
	v_pk_fma_f32 v[32:33], v[88:89], s[8:9], v[32:33] op_sel_hi:[1,0,1]
	v_pk_fma_f32 v[34:35], v[86:87], s[8:9], v[34:35] op_sel_hi:[1,0,1]
	v_add_f32_e32 v78, v46, v47
	v_add_f32_e32 v80, v44, v45
	v_mov_b32_e32 v77, v34
	v_mov_b32_e32 v75, v35
	v_mov_b32_e32 v79, v32
	v_mov_b32_e32 v81, v33
	v_pk_add_f32 v[74:75], v[76:77], v[74:75]
	v_pk_add_f32 v[76:77], v[78:79], v[80:81]
	s_nop 0
	v_pk_add_f32 v[74:75], v[74:75], v[76:77]
	s_nop 0
	v_add_f32_e32 v1, v74, v75
	ds_bpermute_b32 v74, v66, v1
	s_waitcnt lgkmcnt(0)
	v_add_f32_e32 v1, v1, v74
	ds_bpermute_b32 v74, v67, v1
	s_waitcnt lgkmcnt(0)
	v_add_f32_e32 v1, v1, v74
	ds_bpermute_b32 v74, v68, v1
	s_waitcnt lgkmcnt(0)
	v_add_f32_e32 v1, v1, v74
	ds_bpermute_b32 v74, v69, v1
	s_waitcnt lgkmcnt(0)
	v_add_f32_e32 v1, v1, v74
	ds_bpermute_b32 v74, v70, v1
	s_waitcnt lgkmcnt(0)
	v_add_f32_e32 v1, v1, v74
	ds_bpermute_b32 v74, v71, v1
	s_waitcnt lgkmcnt(0)
; __device__ __forceinline__ void phase_ln(const float* res, const bf16_t* br, float* out, const float* gam, const float* bet, bf16_t* xb) {
;     ...
;         const float mu = wave_sum(s) * (1.0f / DM); float q = 0.f;
; #pragma unroll
;         for (int j = 0; j < 8; ++j) { v[j] = v[j] - mu; q += (v[j][0] * v[j][0] + v[j][1] * v[j][1]) + (v[j][2] * v[j][2] + v[j][3] * v[j][3]); }
;         const float rstd = 1.0f / sqrtf(wave_sum(q) * (1.0f / DM) + LN_EPS);
	v_add_f32_e32 v1, v1, v74
	v_fmamk_f32 v65, v1, 0xba000000, v65
	v_fmamk_f32 v61, v1, 0xba000000, v61
	v_fmamk_f32 v63, v1, 0xba000000, v63
	v_fmac_f32_e32 v64, 0xba000000, v1
	v_fmamk_f32 v59, v1, 0xba000000, v59
	v_fmac_f32_e32 v60, 0xba000000, v1
	v_mov_b32_e32 v76, v65
	v_mov_b32_e32 v77, v61
	v_fmac_f32_e32 v62, 0xba000000, v1
	v_fmac_f32_e32 v58, 0xba000000, v1
	v_mov_b32_e32 v74, v64
	v_mov_b32_e32 v75, v60
	v_pk_mul_f32 v[76:77], v[76:77], v[76:77]
	v_mov_b32_e32 v78, v63
	v_mov_b32_e32 v79, v59
	v_pk_fma_f32 v[74:75], v[74:75], v[74:75], v[76:77]
	v_mov_b32_e32 v76, v62
	v_mov_b32_e32 v77, v58
	v_pk_mul_f32 v[78:79], v[78:79], v[78:79]
	v_fmamk_f32 v57, v1, 0xba000000, v57
	v_pk_fma_f32 v[76:77], v[76:77], v[76:77], v[78:79]
	v_fmac_f32_e32 v56, 0xba000000, v1
	v_pk_add_f32 v[74:75], v[74:75], v[76:77]
	v_fmamk_f32 v55, v1, 0xba000000, v55
	v_fmac_f32_e32 v54, 0xba000000, v1
	v_pk_add_f32 v[74:75], v[74:75], v[74:75] op_sel_hi:[0,1]
	v_pk_mul_f32 v[76:77], v[54:55], v[54:55]
	v_pk_mul_f32 v[78:79], v[56:57], v[56:57]
	v_fmac_f32_e32 v52, 0xba000000, v1
	v_pk_mov_b32 v[80:81], v[78:79], v[76:77] op_sel:[1,0]
	v_mov_b32_e32 v79, v77
	v_fmamk_f32 v53, v1, 0xba000000, v53
	v_fmac_f32_e32 v50, 0xba000000, v1
	v_mul_f32_e32 v74, v52, v52
	v_pk_add_f32 v[76:77], v[80:81], v[78:79]
	v_fmamk_f32 v51, v1, 0xba000000, v51
	v_pk_fma_f32 v[78:79], v[52:53], v[52:53], v[74:75] op_sel_hi:[1,1,0]
	v_mul_f32_e32 v74, v50, v50
	v_pk_add_f32 v[76:77], v[76:77], v[76:77] op_sel_hi:[0,1]
	v_pk_fma_f32 v[80:81], v[50:51], v[50:51], v[74:75] op_sel_hi:[1,1,0]
	v_fmamk_f32 v41, v1, 0xba000000, v41
	v_fmac_f32_e32 v40, 0xba000000, v1
	v_fmamk_f32 v43, v1, 0xba000000, v43
	v_fmac_f32_e32 v42, 0xba000000, v1
	v_mul_f32_e32 v78, v42, v42
	v_mul_f32_e32 v80, v43, v43
	v_mul_f32_e32 v76, v40, v40
	v_mul_f32_e32 v74, v41, v41
	v_pk_add_f32 v[78:79], v[78:79], v[80:81]
	v_pk_add_f32 v[74:75], v[76:77], v[74:75]
	v_fmamk_f32 v37, v1, 0xba000000, v37
	v_pk_add_f32 v[74:75], v[78:79], v[74:75]
	v_fmac_f32_e32 v36, 0xba000000, v1
	v_fmamk_f32 v39, v1, 0xba000000, v39
	v_fmac_f32_e32 v38, 0xba000000, v1
	v_pk_add_f32 v[74:75], v[74:75], v[74:75] op_sel_hi:[0,1]
	v_pk_mul_f32 v[76:77], v[38:39], v[38:39]
	v_pk_mul_f32 v[78:79], v[36:37], v[36:37]
	v_fmac_f32_e32 v46, 0xba000000, v1
	v_pk_mov_b32 v[80:81], v[78:79], v[76:77] op_sel:[1,0]
	v_mov_b32_e32 v79, v77
	v_fmamk_f32 v47, v1, 0xba000000, v47
	v_fmac_f32_e32 v44, 0xba000000, v1
	v_mul_f32_e32 v74, v46, v46
	v_pk_add_f32 v[76:77], v[80:81], v[78:79]
	v_fmamk_f32 v45, v1, 0xba000000, v45
	v_pk_fma_f32 v[78:79], v[46:47], v[46:47], v[74:75] op_sel_hi:[1,1,0]
	v_mul_f32_e32 v74, v44, v44
	v_pk_add_f32 v[76:77], v[76:77], v[76:77] op_sel_hi:[0,1]
	v_pk_fma_f32 v[80:81], v[44:45], v[44:45], v[74:75] op_sel_hi:[1,1,0]
	v_fmamk_f32 v33, v1, 0xba000000, v33
	v_fmac_f32_e32 v32, 0xba000000, v1
	v_fmamk_f32 v35, v1, 0xba000000, v35
	v_fmac_f32_e32 v34, 0xba000000, v1
	v_mul_f32_e32 v78, v34, v34
	v_mul_f32_e32 v80, v35, v35
	v_mul_f32_e32 v76, v32, v32
	v_mul_f32_e32 v74, v33, v33
	v_pk_add_f32 v[82:83], v[78:79], v[80:81]
	v_pk_add_f32 v[84:85], v[76:77], v[74:75]
	v_pk_add_f32 v[82:83], v[82:83], v[84:85]
	s_nop 0
	v_add_f32_e32 v1, v82, v83
	ds_bpermute_b32 v82, v66, v1
	s_waitcnt lgkmcnt(0)
	v_add_f32_e32 v1, v1, v82
	ds_bpermute_b32 v82, v67, v1
	s_waitcnt lgkmcnt(0)
	v_add_f32_e32 v1, v1, v82
	ds_bpermute_b32 v82, v68, v1
	s_waitcnt lgkmcnt(0)
	v_add_f32_e32 v1, v1, v82
	ds_bpermute_b32 v82, v69, v1
	s_waitcnt lgkmcnt(0)
	v_add_f32_e32 v1, v1, v82
	ds_bpermute_b32 v82, v70, v1
	s_waitcnt lgkmcnt(0)
	v_add_f32_e32 v1, v1, v82
	ds_bpermute_b32 v82, v71, v1
	s_waitcnt lgkmcnt(0)
; __device__ __forceinline__ unsigned pk2(float lo, float hi) { unsigned r; asm("v_cvt_pk_bf16_f32 %0, %1, %2" : "=v"(r) : "v"(lo), "v"(hi)); return r; }
; __device__ __forceinline__ void phase_ln(const float* res, const bf16_t* br, float* out, const float* gam, const float* bet, bf16_t* xb) {
;     ...
;         const float rstd = 1.0f / sqrtf(wave_sum(q) * (1.0f / DM) + LN_EPS);
;         f32x4* orow = (f32x4*)(out + (size_t)row * DM) + lane;
; #pragma unroll
;         for (int j = 0; j < 8; ++j) { const f32x4 gv = *((const f32x4*)gam + 64 * j + lane), bv = *((const f32x4*)bet + 64 * j + lane);
;             const f32x4 y = v[j] * rstd * gv + bv; __builtin_nontemporal_store(y, orow + 64 * j);
;             if (xb) { u32x2 wv; wv.x = pk2(y[0], y[1]); wv.y = pk2(y[2], y[3]); __builtin_nontemporal_store(wv, (u32x2*)(xb + (size_t)row * DM) + 64 * j + lane); } }
	v_add_f32_e32 v1, v1, v82
	v_fmamk_f32 v1, v1, 0x3a000000, v72
	v_mul_f32_e32 v82, 0x4f800000, v1
	v_cmp_gt_f32_e32 vcc, s11, v1
	s_nop 1
	v_cndmask_b32_e32 v1, v1, v82, vcc
	v_sqrt_f32_e32 v82, v1
	s_nop 0
	v_add_u32_e32 v83, -1, v82
	v_fma_f32 v84, -v83, v82, v1
	v_cmp_ge_f32_e64 s[0:1], 0, v84
	v_add_u32_e32 v84, 1, v82
	s_nop 0
	v_cndmask_b32_e64 v83, v82, v83, s[0:1]
	v_fma_f32 v82, -v84, v82, v1
	v_cmp_lt_f32_e64 s[0:1], 0, v82
	s_nop 1
	v_cndmask_b32_e64 v82, v83, v84, s[0:1]
	v_mul_f32_e32 v83, 0x37800000, v82
	v_cndmask_b32_e32 v82, v82, v83, vcc
	v_cmp_class_f32_e32 vcc, v1, v73
	s_nop 1
	v_cndmask_b32_e32 v1, v82, v1, vcc
	v_div_scale_f32 v82, s[0:1], v1, v1, 1.0
	v_rcp_f32_e32 v83, v82
	s_nop 0
	v_fma_f32 v84, -v82, v83, 1.0
	v_fmac_f32_e32 v83, v84, v83
	v_div_scale_f32 v84, vcc, 1.0, v1, 1.0
	v_mul_f32_e32 v85, v84, v83
	v_fma_f32 v86, -v82, v85, v84
	v_fmac_f32_e32 v85, v86, v83
	v_fma_f32 v82, -v82, v85, v84
	v_div_fmas_f32 v82, v82, v83, v85
	v_div_fixup_f32 v82, v82, v1, 1.0
	v_lshl_add_u64 v[84:85], v[6:7], 0, v[48:49]
	v_lshl_add_u64 v[86:87], v[12:13], 0, v[30:31]
	v_pk_mul_f32 v[30:31], v[64:65], v[82:83] op_sel_hi:[1,0]
	v_pk_mul_f32 v[48:49], v[62:63], v[82:83] op_sel_hi:[1,0]
	v_pk_fma_f32 v[62:63], v[160:161], v[30:31], v[164:165]
	v_pk_fma_f32 v[64:65], v[162:163], v[48:49], v[166:167]
	global_store_dwordx4 v[84:85], v[62:65], off nt
	v_cvt_pk_bf16_f32 v30, v62, v63
	v_cvt_pk_bf16_f32 v31, v64, v65
	global_store_dwordx2 v[86:87], v[30:31], off
	v_pk_mul_f32 v[30:31], v[60:61], v[82:83] op_sel_hi:[1,0]
	v_pk_mul_f32 v[48:49], v[58:59], v[82:83] op_sel_hi:[1,0]
	v_pk_mul_f32 v[40:41], v[40:41], v[82:83] op_sel_hi:[1,0]
	v_pk_mul_f32 v[44:45], v[44:45], v[82:83] op_sel_hi:[1,0]
	v_pk_mul_f32 v[32:33], v[32:33], v[82:83] op_sel_hi:[1,0]
	v_pk_fma_f32 v[60:61], v[170:171], v[48:49], v[174:175]
	v_pk_fma_f32 v[58:59], v[168:169], v[30:31], v[172:173]
	global_store_dwordx4 v[84:85], v[58:61], off offset:1024 nt
	v_cvt_pk_bf16_f32 v30, v58, v59
	v_cvt_pk_bf16_f32 v31, v60, v61
	global_store_dwordx2 v[86:87], v[30:31], off offset:512
	v_pk_mul_f32 v[30:31], v[56:57], v[82:83] op_sel_hi:[1,0]
	v_pk_mul_f32 v[48:49], v[54:55], v[82:83] op_sel_hi:[1,0]
	v_pk_fma_f32 v[54:55], v[176:177], v[30:31], v[180:181]
	v_pk_fma_f32 v[56:57], v[178:179], v[48:49], v[182:183]
	global_store_dwordx4 v[84:85], v[54:57], off offset:2048 nt
	v_cvt_pk_bf16_f32 v30, v54, v55
	v_cvt_pk_bf16_f32 v31, v56, v57
	global_store_dwordx2 v[86:87], v[30:31], off offset:1024
	v_pk_mul_f32 v[30:31], v[52:53], v[82:83] op_sel_hi:[1,0]
	v_pk_mul_f32 v[48:49], v[50:51], v[82:83] op_sel_hi:[1,0]
	v_pk_fma_f32 v[50:51], v[186:187], v[48:49], v[190:191]
	v_pk_fma_f32 v[48:49], v[184:185], v[30:31], v[188:189]
	global_store_dwordx4 v[84:85], v[48:51], off offset:3072 nt
	v_cvt_pk_bf16_f32 v30, v48, v49
	v_cvt_pk_bf16_f32 v31, v50, v51
	global_store_dwordx2 v[86:87], v[30:31], off offset:1536
	v_add_co_u32_e32 v56, vcc, s10, v84
	v_pk_mul_f32 v[30:31], v[42:43], v[82:83] op_sel_hi:[1,0]
	s_nop 0
	v_addc_co_u32_e32 v57, vcc, 0, v85, vcc
	v_cmp_lt_i32_e32 vcc, s12, v0
	s_or_b64 s[6:7], vcc, s[6:7]
	v_pk_fma_f32 v[42:43], v[194:195], v[40:41], v[198:199]
	v_pk_fma_f32 v[40:41], v[192:193], v[30:31], v[196:197]
	global_store_dwordx4 v[56:57], v[40:43], off nt
	v_cvt_pk_bf16_f32 v30, v40, v41
	v_cvt_pk_bf16_f32 v31, v42, v43
	global_store_dwordx2 v[86:87], v[30:31], off offset:2048
	v_pk_mul_f32 v[30:31], v[36:37], v[82:83] op_sel_hi:[1,0]
	v_pk_mul_f32 v[36:37], v[38:39], v[82:83] op_sel_hi:[1,0]
	v_pk_fma_f32 v[38:39], v[202:203], v[36:37], v[206:207]
	v_pk_fma_f32 v[36:37], v[200:201], v[30:31], v[204:205]
	global_store_dwordx4 v[56:57], v[36:39], off offset:1024 nt
	v_cvt_pk_bf16_f32 v30, v36, v37
	v_cvt_pk_bf16_f32 v31, v38, v39
	global_store_dwordx2 v[86:87], v[30:31], off offset:2560
	v_pk_mul_f32 v[30:31], v[46:47], v[82:83] op_sel_hi:[1,0]
	v_pk_fma_f32 v[38:39], v[44:45], v[210:211], v[214:215]
	v_pk_fma_f32 v[36:37], v[30:31], v[208:209], v[212:213]
	global_store_dwordx4 v[56:57], v[36:39], off offset:2048 nt
	v_cvt_pk_bf16_f32 v30, v36, v37
	v_cvt_pk_bf16_f32 v31, v38, v39
	global_store_dwordx2 v[86:87], v[30:31], off offset:3072
	v_pk_mul_f32 v[30:31], v[34:35], v[82:83] op_sel_hi:[1,0]
	v_pk_fma_f32 v[32:33], v[32:33], v[218:219], v[222:223]
	v_pk_fma_f32 v[30:31], v[30:31], v[216:217], v[220:221]
	global_store_dwordx4 v[56:57], v[30:33], off offset:3072 nt
	s_nop 1
	v_cvt_pk_bf16_f32 v30, v30, v31
	v_cvt_pk_bf16_f32 v31, v32, v33
	global_store_dwordx2 v[86:87], v[30:31], off offset:3584
	s_andn2_b64 exec, exec, s[6:7]
	s_cbranch_execnz .LBB0_814

; __device__ __forceinline__ unsigned pk2(float lo, float hi) { unsigned r; asm("v_cvt_pk_bf16_f32 %0, %1, %2" : "=v"(r) : "v"(lo), "v"(hi)); return r; }
; __device__ __forceinline__ void phase_ln(const float* res, const bf16_t* br, float* out, const float* gam, const float* bet, bf16_t* xb) {
;     const int tid = threadIdx.x, lane = tid & 63, wave = tid >> 6;
;     for (int row = blockIdx.x * NWAVES + wave; row < T; row += gridDim.x * NWAVES) {
;         const f32x4* xr = (const f32x4*)(res + (size_t)row * DM) + lane; const u32x2* brr = (const u32x2*)(br + (size_t)row * DM) + lane;
;         f32x4 v[8]; float s = 0.f;
; #pragma unroll
;         for (int j = 0; j < 8; ++j) { const f32x4 xv = __builtin_nontemporal_load(xr + 64 * j); const u32x2 bw = __builtin_nontemporal_load(brr + 64 * j);
;             v[j] = xv * ALPHA + (f32x4){bflo(bw.x), bfhi(bw.x), bflo(bw.y), bfhi(bw.y)}; s += (v[j][0] + v[j][1]) + (v[j][2] + v[j][3]); }
;         const float mu = wave_sum(s) * (1.0f / DM); float q = 0.f;
; #pragma unroll
;         for (int j = 0; j < 8; ++j) { v[j] = v[j] - mu; q += (v[j][0] * v[j][0] + v[j][1] * v[j][1]) + (v[j][2] * v[j][2] + v[j][3] * v[j][3]); }
;         const float rstd = 1.0f / sqrtf(wave_sum(q) * (1.0f / DM) + LN_EPS);
;         f32x4* orow = (f32x4*)(out + (size_t)row * DM) + lane;
; #pragma unroll
;         for (int j = 0; j < 8; ++j) { const f32x4 gv = *((const f32x4*)gam + 64 * j + lane), bv = *((const f32x4*)bet + 64 * j + lane);
;             const f32x4 y = v[j] * rstd * gv + bv; __builtin_nontemporal_store(y, orow + 64 * j);
;             if (xb) { u32x2 wv; wv.x = pk2(y[0], y[1]); wv.y = pk2(y[2], y[3]); __builtin_nontemporal_store(wv, (u32x2*)(xb + (size_t)row * DM) + 64 * j + lane); } }
.LBB0_1121:
	v_readlane_b32 s4, v246, 12
	s_cmp_lt_i32 s4, 13
	s_cselect_b64 s[2:3], -1, 0
	s_and_b64 s[0:1], s[2:3], s[0:1]
	s_andn2_b64 vcc, exec, s[0:1]
	v_readlane_b32 s5, v246, 13
	v_readlane_b32 s6, v246, 14
	v_readlane_b32 s7, v246, 15
	s_cbranch_vccnz .LBB0_1125
	v_readlane_b32 s0, v246, 0
	v_readlane_b32 s1, v246, 1
	s_waitcnt vmcnt(0)
	v_lshl_add_u32 v0, s0, 3, v159
	s_mov_b32 s0, 0x8000
	v_cmp_gt_i32_e32 vcc, s0, v0
	s_and_saveexec_b64 s[0:1], vcc
	s_cbranch_execz .LBB0_1125
	v_and_b32_e32 v1, 63, v144
	v_lshlrev_b32_e32 v8, 4, v1
	v_lshlrev_b32_e32 v4, 3, v1
	v_mbcnt_lo_u32_b32 v1, -1, 0
	v_mbcnt_hi_u32_b32 v1, -1, v1
	v_and_b32_e32 v6, 64, v1
	v_add_u32_e32 v6, 64, v6
	v_xor_b32_e32 v7, 1, v1
	v_cmp_lt_i32_e32 vcc, v7, v6
	v_readlane_b32 s0, v246, 2
	v_readlane_b32 s1, v246, 3
	v_cndmask_b32_e32 v7, v1, v7, vcc
	v_lshlrev_b32_e32 v62, 2, v7
	v_xor_b32_e32 v7, 2, v1
	v_cmp_lt_i32_e32 vcc, v7, v6
	v_mov_b32_e32 v9, 0
	v_readlane_b32 s0, v246, 10
	v_cndmask_b32_e32 v7, v1, v7, vcc
	v_lshlrev_b32_e32 v63, 2, v7
	v_xor_b32_e32 v7, 4, v1
	v_cmp_lt_i32_e32 vcc, v7, v6
	v_mov_b32_e32 v5, v9
	v_readlane_b32 s1, v246, 11
	v_cndmask_b32_e32 v7, v1, v7, vcc
	v_lshlrev_b32_e32 v64, 2, v7
	v_xor_b32_e32 v7, 8, v1
	v_cmp_lt_i32_e32 vcc, v7, v6
	v_readlane_b32 s2, v246, 4
	v_readlane_b32 s3, v246, 5
	v_cndmask_b32_e32 v7, v1, v7, vcc
	v_lshlrev_b32_e32 v65, 2, v7
	v_xor_b32_e32 v7, 16, v1
	v_cmp_lt_i32_e32 vcc, v7, v6
	v_readlane_b32 s4, v246, 6
	v_readlane_b32 s5, v246, 7
	v_cndmask_b32_e32 v7, v1, v7, vcc
	v_lshlrev_b32_e32 v66, 2, v7
	v_xor_b32_e32 v7, 32, v1
	v_readlane_b32 s6, v246, 8
	v_readlane_b32 s7, v246, 9
	v_lshl_add_u64 v[4:5], s[0:1], 0, v[4:5]
	s_mov_b64 s[0:1], 0x8800000
	v_cmp_lt_i32_e32 vcc, v7, v6
	s_waitcnt lgkmcnt(0)
	v_lshl_add_u64 v[2:3], s[6:7], 0, v[8:9]
	v_lshl_add_u64 v[4:5], v[4:5], 0, s[0:1]
	v_cndmask_b32_e32 v1, v1, v7, vcc
	v_lshl_add_u64 v[6:7], s[2:3], 0, v[8:9]
	v_lshl_add_u64 v[8:9], s[4:5], 0, v[8:9]
	s_mov_b64 s[0:1], 0x1000
	v_lshl_add_u64 v[10:11], v[6:7], 0, s[0:1]
	v_lshl_add_u64 v[12:13], v[8:9], 0, s[0:1]
	s_mov_b64 s[0:1], 0x1400
	v_lshl_add_u64 v[14:15], v[6:7], 0, s[0:1]
	v_lshl_add_u64 v[16:17], v[8:9], 0, s[0:1]
	s_mov_b64 s[0:1], 0x1800
	v_lshl_add_u64 v[18:19], v[6:7], 0, s[0:1]
	v_lshl_add_u64 v[20:21], v[8:9], 0, s[0:1]
	s_mov_b64 s[0:1], 0x1c00
	v_lshlrev_b32_e32 v67, 2, v1
	v_lshl_add_u64 v[22:23], v[6:7], 0, s[0:1]
	v_lshl_add_u64 v[24:25], v[8:9], 0, s[0:1]
	s_lshl_b32 s5, s34, 3
	s_mov_b64 s[2:3], 0
	s_mov_b32 s4, 0x3f9837f0
	s_movk_i32 s6, 0x1000
	v_mov_b32_e32 v68, 0x3727c5ac
	s_mov_b32 s7, 0xf800000
	v_mov_b32_e32 v69, 0x260
	s_movk_i32 s8, 0x7fff
	global_load_dwordx4 v[160:163], v[6:7], off
	global_load_dwordx4 v[164:167], v[8:9], off
	global_load_dwordx4 v[168:171], v[6:7], off offset:1024
	global_load_dwordx4 v[172:175], v[8:9], off offset:1024
	global_load_dwordx4 v[176:179], v[6:7], off offset:2048
	global_load_dwordx4 v[180:183], v[8:9], off offset:2048
	global_load_dwordx4 v[184:187], v[6:7], off offset:3072
	global_load_dwordx4 v[188:191], v[8:9], off offset:3072
	global_load_dwordx4 v[192:195], v[10:11], off
	global_load_dwordx4 v[196:199], v[12:13], off
	global_load_dwordx4 v[200:203], v[14:15], off
	global_load_dwordx4 v[204:207], v[16:17], off
	global_load_dwordx4 v[208:211], v[18:19], off
	global_load_dwordx4 v[212:215], v[20:21], off
	global_load_dwordx4 v[216:219], v[22:23], off
	global_load_dwordx4 v[220:223], v[24:25], off
	s_waitcnt vmcnt(0)
.LBB0_1124:
	v_ashrrev_i32_e32 v1, 31, v0
	v_lshlrev_b64 v[26:27], 12, v[0:1]
	v_lshl_add_u64 v[46:47], v[4:5], 0, v[26:27]
	v_lshlrev_b64 v[26:27], 13, v[0:1]
	global_load_dwordx2 v[48:49], v[46:47], off nt
	global_load_dwordx2 v[50:51], v[46:47], off offset:512 nt
	global_load_dwordx2 v[52:53], v[46:47], off offset:1024 nt
	global_load_dwordx2 v[54:55], v[46:47], off offset:1536 nt
	global_load_dwordx2 v[56:57], v[46:47], off offset:2048 nt
	global_load_dwordx2 v[58:59], v[46:47], off offset:2560 nt
	v_lshl_add_u64 v[28:29], v[2:3], 0, v[26:27]
	global_load_dwordx4 v[30:33], v[28:29], off nt
	global_load_dwordx4 v[34:37], v[28:29], off offset:1024 nt
	global_load_dwordx4 v[38:41], v[28:29], off offset:2048 nt
	global_load_dwordx4 v[42:45], v[28:29], off offset:3072 nt
	v_add_co_u32_e32 v26, vcc, s6, v28
	v_add_u32_e32 v0, s5, v0
	s_nop 0
	v_addc_co_u32_e32 v27, vcc, 0, v29, vcc
	global_load_dwordx4 v[70:73], v[26:27], off nt
	global_load_dwordx4 v[74:77], v[26:27], off offset:1024 nt
	global_load_dwordx2 v[86:87], v[46:47], off offset:3072 nt
	global_load_dwordx4 v[78:81], v[26:27], off offset:2048 nt
	global_load_dwordx2 v[88:89], v[46:47], off offset:3584 nt
	global_load_dwordx4 v[82:85], v[26:27], off offset:3072 nt
	s_waitcnt vmcnt(15)
	v_lshlrev_b32_e32 v46, 16, v48
	v_and_b32_e32 v47, 0xffff0000, v48
	v_lshlrev_b32_e32 v48, 16, v49
	v_and_b32_e32 v49, 0xffff0000, v49
	s_waitcnt vmcnt(14)
	v_lshlrev_b32_e32 v90, 16, v50
	v_and_b32_e32 v91, 0xffff0000, v50
	v_lshlrev_b32_e32 v50, 16, v51
	v_and_b32_e32 v51, 0xffff0000, v51
	s_waitcnt vmcnt(13)
	v_lshlrev_b32_e32 v92, 16, v52
	v_and_b32_e32 v93, 0xffff0000, v52
	v_lshlrev_b32_e32 v52, 16, v53
	v_and_b32_e32 v53, 0xffff0000, v53
	s_waitcnt vmcnt(12)
	v_lshlrev_b32_e32 v94, 16, v54
	v_and_b32_e32 v95, 0xffff0000, v54
	v_lshlrev_b32_e32 v96, 16, v55
	v_and_b32_e32 v97, 0xffff0000, v55
	s_waitcnt vmcnt(11)
	v_lshlrev_b32_e32 v98, 16, v56
	v_and_b32_e32 v99, 0xffff0000, v56
	v_lshlrev_b32_e32 v100, 16, v57
	v_and_b32_e32 v101, 0xffff0000, v57
	s_waitcnt vmcnt(10)
	v_lshlrev_b32_e32 v102, 16, v58
	v_and_b32_e32 v103, 0xffff0000, v58
	v_lshlrev_b32_e32 v104, 16, v59
	v_and_b32_e32 v105, 0xffff0000, v59
	s_waitcnt vmcnt(9)
; __device__ __forceinline__ void phase_ln(const float* res, const bf16_t* br, float* out, const float* gam, const float* bet, bf16_t* xb) {
;     ...
;         const f32x4* xr = (const f32x4*)(res + (size_t)row * DM) + lane; const u32x2* brr = (const u32x2*)(br + (size_t)row * DM) + lane;
;         f32x4 v[8]; float s = 0.f;
; #pragma unroll
;         for (int j = 0; j < 8; ++j) { const f32x4 xv = __builtin_nontemporal_load(xr + 64 * j); const u32x2 bw = __builtin_nontemporal_load(brr + 64 * j);
;             v[j] = xv * ALPHA + (f32x4){bflo(bw.x), bfhi(bw.x), bflo(bw.y), bfhi(bw.y)}; s += (v[j][0] + v[j][1]) + (v[j][2] + v[j][3]); }
;         const float mu = wave_sum(s) * (1.0f / DM); float q = 0.f;
; #pragma unroll
;         for (int j = 0; j < 8; ++j) { v[j] = v[j] - mu; q += (v[j][0] * v[j][0] + v[j][1] * v[j][1]) + (v[j][2] * v[j][2] + v[j][3] * v[j][3]); }
;         const float rstd = 1.0f / sqrtf(wave_sum(q) * (1.0f / DM) + LN_EPS);
	v_pk_fma_f32 v[58:59], v[32:33], s[4:5], v[48:49] op_sel_hi:[1,0,1]
	v_pk_fma_f32 v[60:61], v[30:31], s[4:5], v[46:47] op_sel_hi:[1,0,1]
	s_waitcnt vmcnt(8)
	v_pk_fma_f32 v[54:55], v[36:37], s[4:5], v[50:51] op_sel_hi:[1,0,1]
	v_pk_fma_f32 v[56:57], v[34:35], s[4:5], v[90:91] op_sel_hi:[1,0,1]
	s_waitcnt vmcnt(7)
	v_pk_fma_f32 v[52:53], v[40:41], s[4:5], v[52:53] op_sel_hi:[1,0,1]
	v_pk_fma_f32 v[50:51], v[38:39], s[4:5], v[92:93] op_sel_hi:[1,0,1]
	s_waitcnt vmcnt(6)
	v_pk_fma_f32 v[48:49], v[44:45], s[4:5], v[96:97] op_sel_hi:[1,0,1]
	v_pk_fma_f32 v[46:47], v[42:43], s[4:5], v[94:95] op_sel_hi:[1,0,1]
	v_mov_b32_e32 v34, v60
	v_mov_b32_e32 v35, v56
	v_mov_b32_e32 v36, v61
	v_mov_b32_e32 v37, v57
	v_mov_b32_e32 v42, v58
	v_mov_b32_e32 v43, v54
	v_mov_b32_e32 v44, v59
	v_mov_b32_e32 v45, v55
	s_waitcnt vmcnt(5)
	v_pk_fma_f32 v[40:41], v[72:73], s[4:5], v[100:101] op_sel_hi:[1,0,1]
	v_pk_fma_f32 v[38:39], v[70:71], s[4:5], v[98:99] op_sel_hi:[1,0,1]
	v_pk_mov_b32 v[70:71], v[50:51], v[52:53] op_sel:[1,0]
	v_mov_b32_e32 v72, v50
	v_mov_b32_e32 v73, v53
	v_pk_add_f32 v[34:35], v[34:35], v[36:37]
	v_pk_add_f32 v[36:37], v[42:43], v[44:45]
	v_pk_add_f32 v[42:43], v[70:71], v[72:73]
	v_pk_add_f32 v[34:35], v[34:35], v[36:37]
	v_pk_add_f32 v[36:37], v[42:43], v[42:43] op_sel:[0,1] op_sel_hi:[1,0]
	v_add_f32_e32 v1, 0, v34
	s_waitcnt vmcnt(4)
	v_pk_fma_f32 v[30:31], v[74:75], s[4:5], v[102:103] op_sel_hi:[1,0,1]
	v_pk_fma_f32 v[32:33], v[76:77], s[4:5], v[104:105] op_sel_hi:[1,0,1]
	v_add_f32_e32 v74, v46, v47
	v_add_f32_e32 v76, v48, v49
	v_mov_b32_e32 v91, v38
	v_mov_b32_e32 v75, v40
	v_mov_b32_e32 v77, v41
	v_mov_b32_e32 v37, v39
	v_add_f32_e32 v90, v1, v35
	v_pk_add_f32 v[44:45], v[74:75], v[76:77]
	v_pk_add_f32 v[34:35], v[90:91], v[36:37]
	v_pk_mov_b32 v[92:93], v[30:31], v[32:33] op_sel:[1,0]
	v_pk_add_f32 v[34:35], v[34:35], v[44:45]
	v_mov_b32_e32 v94, v30
	v_mov_b32_e32 v95, v33
	v_pk_add_f32 v[72:73], v[34:35], v[34:35] op_sel:[0,1] op_sel_hi:[1,0]
	s_waitcnt vmcnt(3)
	v_lshlrev_b32_e32 v34, 16, v86
	v_and_b32_e32 v35, 0xffff0000, v86
	v_lshlrev_b32_e32 v36, 16, v87
	v_and_b32_e32 v37, 0xffff0000, v87
	v_pk_add_f32 v[70:71], v[92:93], v[94:95]
	s_waitcnt vmcnt(2)
	v_pk_fma_f32 v[44:45], v[80:81], s[4:5], v[36:37] op_sel_hi:[1,0,1]
	v_pk_fma_f32 v[42:43], v[78:79], s[4:5], v[34:35] op_sel_hi:[1,0,1]
	s_waitcnt vmcnt(1)
	v_lshlrev_b32_e32 v36, 16, v88
	v_and_b32_e32 v37, 0xffff0000, v88
	v_lshlrev_b32_e32 v34, 16, v89
	v_and_b32_e32 v35, 0xffff0000, v89
	v_pk_add_f32 v[70:71], v[70:71], v[70:71] op_sel:[0,1] op_sel_hi:[1,0]
	s_waitcnt vmcnt(0)
	v_pk_fma_f32 v[34:35], v[84:85], s[4:5], v[34:35] op_sel_hi:[1,0,1]
	v_pk_fma_f32 v[36:37], v[82:83], s[4:5], v[36:37] op_sel_hi:[1,0,1]
	v_add_f32_e32 v74, v42, v43
	v_add_f32_e32 v76, v44, v45
	v_mov_b32_e32 v73, v36
	v_mov_b32_e32 v71, v37
	v_mov_b32_e32 v75, v34
	v_mov_b32_e32 v77, v35
	v_pk_add_f32 v[70:71], v[72:73], v[70:71]
	v_pk_add_f32 v[72:73], v[74:75], v[76:77]
	s_nop 0
	v_pk_add_f32 v[70:71], v[70:71], v[72:73]
	s_nop 0
	v_add_f32_e32 v1, v70, v71
	ds_bpermute_b32 v70, v62, v1
	s_waitcnt lgkmcnt(0)
	v_add_f32_e32 v1, v1, v70
	ds_bpermute_b32 v70, v63, v1
	s_waitcnt lgkmcnt(0)
	v_add_f32_e32 v1, v1, v70
	ds_bpermute_b32 v70, v64, v1
	s_waitcnt lgkmcnt(0)
	v_add_f32_e32 v1, v1, v70
	ds_bpermute_b32 v70, v65, v1
	s_waitcnt lgkmcnt(0)
	v_add_f32_e32 v1, v1, v70
	ds_bpermute_b32 v70, v66, v1
	s_waitcnt lgkmcnt(0)
	v_add_f32_e32 v1, v1, v70
	ds_bpermute_b32 v70, v67, v1
	s_waitcnt lgkmcnt(0)
	v_add_f32_e32 v1, v1, v70
	v_fmamk_f32 v61, v1, 0xba000000, v61
	v_fmamk_f32 v57, v1, 0xba000000, v57
	v_fmamk_f32 v59, v1, 0xba000000, v59
	v_fmac_f32_e32 v60, 0xba000000, v1
	v_fmamk_f32 v55, v1, 0xba000000, v55
	v_fmac_f32_e32 v56, 0xba000000, v1
	v_mov_b32_e32 v72, v61
	v_mov_b32_e32 v73, v57
	v_fmac_f32_e32 v58, 0xba000000, v1
	v_fmac_f32_e32 v54, 0xba000000, v1
	v_mov_b32_e32 v70, v60
	v_mov_b32_e32 v71, v56
	v_pk_mul_f32 v[72:73], v[72:73], v[72:73]
	v_mov_b32_e32 v74, v59
	v_mov_b32_e32 v75, v55
	v_pk_fma_f32 v[70:71], v[70:71], v[70:71], v[72:73]
	v_mov_b32_e32 v72, v58
	v_mov_b32_e32 v73, v54
	v_pk_mul_f32 v[74:75], v[74:75], v[74:75]
	v_fmamk_f32 v51, v1, 0xba000000, v51
	v_pk_fma_f32 v[72:73], v[72:73], v[72:73], v[74:75]
	v_fmac_f32_e32 v50, 0xba000000, v1
	v_pk_add_f32 v[70:71], v[70:71], v[72:73]
	v_fmamk_f32 v53, v1, 0xba000000, v53
	v_fmac_f32_e32 v52, 0xba000000, v1
	v_pk_add_f32 v[70:71], v[70:71], v[70:71] op_sel_hi:[0,1]
	v_pk_mul_f32 v[72:73], v[52:53], v[52:53]
	v_pk_mul_f32 v[74:75], v[50:51], v[50:51]
	v_fmac_f32_e32 v46, 0xba000000, v1
	v_pk_mov_b32 v[76:77], v[74:75], v[72:73] op_sel:[1,0]
	v_mov_b32_e32 v75, v73
	v_fmamk_f32 v47, v1, 0xba000000, v47
	v_fmac_f32_e32 v48, 0xba000000, v1
	v_mul_f32_e32 v70, v46, v46
	v_pk_add_f32 v[72:73], v[76:77], v[74:75]
	v_fmamk_f32 v49, v1, 0xba000000, v49
	v_pk_fma_f32 v[74:75], v[46:47], v[46:47], v[70:71] op_sel_hi:[1,1,0]
	v_mul_f32_e32 v70, v48, v48
	v_pk_add_f32 v[72:73], v[72:73], v[72:73] op_sel_hi:[0,1]
	v_pk_fma_f32 v[76:77], v[48:49], v[48:49], v[70:71] op_sel_hi:[1,1,0]
	v_fmamk_f32 v41, v1, 0xba000000, v41
	v_fmac_f32_e32 v40, 0xba000000, v1
	v_fmamk_f32 v39, v1, 0xba000000, v39
	v_fmac_f32_e32 v38, 0xba000000, v1
	v_mul_f32_e32 v74, v38, v38
	v_mul_f32_e32 v76, v39, v39
	v_mul_f32_e32 v72, v40, v40
	v_mul_f32_e32 v70, v41, v41
	v_pk_add_f32 v[74:75], v[74:75], v[76:77]
	v_pk_add_f32 v[70:71], v[72:73], v[70:71]
	v_fmamk_f32 v31, v1, 0xba000000, v31
	v_pk_add_f32 v[70:71], v[74:75], v[70:71]
	v_fmac_f32_e32 v30, 0xba000000, v1
	v_fmamk_f32 v33, v1, 0xba000000, v33
	v_fmac_f32_e32 v32, 0xba000000, v1
	v_pk_add_f32 v[78:79], v[70:71], v[70:71] op_sel_hi:[0,1]
	v_pk_mul_f32 v[70:71], v[32:33], v[32:33]
	v_pk_mul_f32 v[72:73], v[30:31], v[30:31]
	v_fmac_f32_e32 v42, 0xba000000, v1
	v_pk_mov_b32 v[74:75], v[72:73], v[70:71] op_sel:[1,0]
	v_mov_b32_e32 v73, v71
	v_pk_add_f32 v[70:71], v[74:75], v[72:73]
	v_fmamk_f32 v43, v1, 0xba000000, v43
	v_pk_add_f32 v[80:81], v[70:71], v[70:71] op_sel_hi:[0,1]
	v_fmac_f32_e32 v44, 0xba000000, v1
	v_mul_f32_e32 v70, v42, v42
	v_fmamk_f32 v45, v1, 0xba000000, v45
	v_pk_fma_f32 v[82:83], v[42:43], v[42:43], v[70:71] op_sel_hi:[1,1,0]
	v_mul_f32_e32 v70, v44, v44
	v_pk_fma_f32 v[84:85], v[44:45], v[44:45], v[70:71] op_sel_hi:[1,1,0]
	v_fmamk_f32 v35, v1, 0xba000000, v35
	v_fmac_f32_e32 v34, 0xba000000, v1
	v_fmamk_f32 v37, v1, 0xba000000, v37
	v_fmac_f32_e32 v36, 0xba000000, v1
	v_mul_f32_e32 v82, v36, v36
	v_mul_f32_e32 v84, v37, v37
	v_mul_f32_e32 v80, v34, v34
	v_mul_f32_e32 v78, v35, v35
	v_pk_add_f32 v[82:83], v[82:83], v[84:85]
	v_pk_add_f32 v[78:79], v[80:81], v[78:79]
	s_nop 0
	v_pk_add_f32 v[78:79], v[82:83], v[78:79]
	s_nop 0
	v_add_f32_e32 v1, v78, v79
	ds_bpermute_b32 v78, v62, v1
	s_waitcnt lgkmcnt(0)
; __device__ __forceinline__ unsigned pk2(float lo, float hi) { unsigned r; asm("v_cvt_pk_bf16_f32 %0, %1, %2" : "=v"(r) : "v"(lo), "v"(hi)); return r; }
; __device__ __forceinline__ void phase_ln(const float* res, const bf16_t* br, float* out, const float* gam, const float* bet, bf16_t* xb) {
;     ...
;         const float rstd = 1.0f / sqrtf(wave_sum(q) * (1.0f / DM) + LN_EPS);
;         f32x4* orow = (f32x4*)(out + (size_t)row * DM) + lane;
; #pragma unroll
;         for (int j = 0; j < 8; ++j) { const f32x4 gv = *((const f32x4*)gam + 64 * j + lane), bv = *((const f32x4*)bet + 64 * j + lane);
;             const f32x4 y = v[j] * rstd * gv + bv; __builtin_nontemporal_store(y, orow + 64 * j);
;             if (xb) { u32x2 wv; wv.x = pk2(y[0], y[1]); wv.y = pk2(y[2], y[3]); __builtin_nontemporal_store(wv, (u32x2*)(xb + (size_t)row * DM) + 64 * j + lane); } }
	v_add_f32_e32 v1, v1, v78
	ds_bpermute_b32 v78, v63, v1
	s_waitcnt lgkmcnt(0)
	v_add_f32_e32 v1, v1, v78
	ds_bpermute_b32 v78, v64, v1
	s_waitcnt lgkmcnt(0)
	v_add_f32_e32 v1, v1, v78
	ds_bpermute_b32 v78, v65, v1
	s_waitcnt lgkmcnt(0)
	v_add_f32_e32 v1, v1, v78
	ds_bpermute_b32 v78, v66, v1
	s_waitcnt lgkmcnt(0)
	v_add_f32_e32 v1, v1, v78
	ds_bpermute_b32 v78, v67, v1
	s_waitcnt lgkmcnt(0)
	v_add_f32_e32 v1, v1, v78
	v_fmamk_f32 v1, v1, 0x3a000000, v68
	v_mul_f32_e32 v78, 0x4f800000, v1
	v_cmp_gt_f32_e32 vcc, s7, v1
	s_nop 1
	v_cndmask_b32_e32 v1, v1, v78, vcc
	v_sqrt_f32_e32 v78, v1
	s_nop 0
	v_add_u32_e32 v79, -1, v78
	v_fma_f32 v80, -v79, v78, v1
	v_cmp_ge_f32_e64 s[0:1], 0, v80
	v_add_u32_e32 v80, 1, v78
	s_nop 0
	v_cndmask_b32_e64 v79, v78, v79, s[0:1]
	v_fma_f32 v78, -v80, v78, v1
	v_cmp_lt_f32_e64 s[0:1], 0, v78
	s_nop 1
	v_cndmask_b32_e64 v78, v79, v80, s[0:1]
	v_mul_f32_e32 v79, 0x37800000, v78
	v_cndmask_b32_e32 v78, v78, v79, vcc
	v_cmp_class_f32_e32 vcc, v1, v69
	s_nop 1
	v_cndmask_b32_e32 v1, v78, v1, vcc
	v_div_scale_f32 v78, s[0:1], v1, v1, 1.0
	v_rcp_f32_e32 v79, v78
	s_nop 0
	v_fma_f32 v80, -v78, v79, 1.0
	v_fmac_f32_e32 v79, v80, v79
	v_div_scale_f32 v80, vcc, 1.0, v1, 1.0
	v_mul_f32_e32 v81, v80, v79
	v_fma_f32 v82, -v78, v81, v80
	v_fmac_f32_e32 v81, v82, v79
	v_fma_f32 v78, -v78, v81, v80
	v_div_fmas_f32 v78, v78, v79, v81
	v_div_fixup_f32 v78, v78, v1, 1.0
	v_pk_mul_f32 v[80:81], v[60:61], v[78:79] op_sel_hi:[1,0]
	v_pk_mul_f32 v[58:59], v[58:59], v[78:79] op_sel_hi:[1,0]
	v_pk_mul_f32 v[52:53], v[52:53], v[78:79] op_sel_hi:[1,0]
	v_pk_fma_f32 v[60:61], v[162:163], v[58:59], v[166:167]
	v_pk_fma_f32 v[58:59], v[160:161], v[80:81], v[164:165]
	global_store_dwordx4 v[28:29], v[58:61], off nt
	s_nop 0
	v_pk_mul_f32 v[74:75], v[54:55], v[78:79] op_sel_hi:[1,0]
	v_pk_mul_f32 v[54:55], v[56:57], v[78:79] op_sel_hi:[1,0]
	v_pk_mul_f32 v[50:51], v[50:51], v[78:79] op_sel_hi:[1,0]
	v_pk_mul_f32 v[48:49], v[48:49], v[78:79] op_sel_hi:[1,0]
	v_pk_mul_f32 v[46:47], v[46:47], v[78:79] op_sel_hi:[1,0]
	v_pk_mul_f32 v[38:39], v[38:39], v[78:79] op_sel_hi:[1,0]
	v_pk_mul_f32 v[32:33], v[32:33], v[78:79] op_sel_hi:[1,0]
	v_pk_mul_f32 v[42:43], v[42:43], v[78:79] op_sel_hi:[1,0]
	v_cmp_lt_i32_e32 vcc, s8, v0
	s_or_b64 s[2:3], vcc, s[2:3]
	v_pk_fma_f32 v[54:55], v[168:169], v[54:55], v[172:173]
	v_pk_fma_f32 v[56:57], v[170:171], v[74:75], v[174:175]
	global_store_dwordx4 v[28:29], v[54:57], off offset:1024 nt
	s_nop 0
	v_pk_fma_f32 v[50:51], v[176:177], v[50:51], v[180:181]
	v_pk_fma_f32 v[52:53], v[178:179], v[52:53], v[182:183]
	global_store_dwordx4 v[28:29], v[50:53], off offset:2048 nt
	s_nop 0
	v_pk_fma_f32 v[46:47], v[184:185], v[46:47], v[188:189]
	v_pk_fma_f32 v[48:49], v[186:187], v[48:49], v[190:191]
	global_store_dwordx4 v[28:29], v[46:49], off offset:3072 nt
	s_nop 0
	v_pk_mul_f32 v[28:29], v[40:41], v[78:79] op_sel_hi:[1,0]
	v_pk_fma_f32 v[38:39], v[192:193], v[38:39], v[196:197]
	v_pk_fma_f32 v[40:41], v[194:195], v[28:29], v[198:199]
	global_store_dwordx4 v[26:27], v[38:41], off nt
	s_nop 0
	v_pk_mul_f32 v[28:29], v[30:31], v[78:79] op_sel_hi:[1,0]
	v_pk_fma_f32 v[30:31], v[202:203], v[32:33], v[206:207]
	v_pk_fma_f32 v[28:29], v[200:201], v[28:29], v[204:205]
	global_store_dwordx4 v[26:27], v[28:31], off offset:1024 nt
	s_nop 0
	v_pk_mul_f32 v[32:33], v[44:45], v[78:79] op_sel_hi:[1,0]
	v_pk_fma_f32 v[28:29], v[208:209], v[42:43], v[212:213]
	v_pk_fma_f32 v[30:31], v[210:211], v[32:33], v[214:215]
	global_store_dwordx4 v[26:27], v[28:31], off offset:2048 nt
	s_nop 0
	v_pk_mul_f32 v[32:33], v[34:35], v[78:79] op_sel_hi:[1,0]
	v_pk_mul_f32 v[34:35], v[36:37], v[78:79] op_sel_hi:[1,0]
	v_pk_fma_f32 v[30:31], v[218:219], v[32:33], v[222:223]
	v_pk_fma_f32 v[28:29], v[216:217], v[34:35], v[220:221]
	global_store_dwordx4 v[26:27], v[28:31], off offset:3072 nt
	s_andn2_b64 exec, exec, s[2:3]
	s_cbranch_execnz .LBB0_1124
